# attention: lane^16 / lane^32 butterfly steps of softmax max and exp-sum via v_permlane16_swap / v_permlane32_swap instead of ds_bpermute
# baseline (speedup 1.0000x reference)
.LBB0_408:
	s_add_i32 s20, s38, s64
	s_and_b32 s20, s20, 0x1c0
	s_lshl_b32 s36, s20, 1
	v_mov_b64_e32 v[86:87], v[26:27]
	v_lshl_add_u64 v[0:1], v[140:141], 0, s[36:37]
	v_mov_b64_e32 v[84:85], v[24:25]
	global_load_dwordx4 v[24:27], v[0:1], off
	global_load_dwordx4 v[32:35], v[0:1], off offset:64
	v_mov_b32_e32 v0, v177
	v_mov_b32_e32 v164, v226
	ds_read_b128 v[40:43], v203
	ds_read_b128 v[44:47], v203 offset:64
	s_waitcnt lgkmcnt(1)
	v_mfma_f32_16x16x32_bf16 v[40:43], v[40:43], v[84:87], 0
	ds_read_b128 v[48:51], v204
	ds_read_b128 v[52:55], v204 offset:64
	v_readlane_b32 s20, v225, s35
	s_waitcnt lgkmcnt(2)
	v_mfma_f32_16x16x32_bf16 v[80:83], v[44:47], v[36:39], v[40:43]
	ds_read_b128 v[44:47], v205 offset:64
	s_nop 1
	ds_read_b128 v[40:43], v205
	s_waitcnt lgkmcnt(3)
	v_mfma_f32_16x16x32_bf16 v[48:51], v[48:51], v[84:87], 0
	s_waitcnt lgkmcnt(2)
	v_mfma_f32_16x16x32_bf16 v[76:79], v[52:55], v[36:39], v[48:51]
	s_waitcnt lgkmcnt(0)
	v_mfma_f32_16x16x32_bf16 v[40:43], v[40:43], v[84:87], 0
	s_nop 3
	ds_read_b128 v[48:51], v206
	v_mfma_f32_16x16x32_bf16 v[72:75], v[44:47], v[36:39], v[40:43]
	s_nop 2
	ds_read_b128 v[40:43], v206 offset:64
	s_waitcnt lgkmcnt(1)
	v_mfma_f32_16x16x32_bf16 v[44:47], v[48:51], v[84:87], 0
	ds_read_b128 v[48:51], v207
	s_waitcnt lgkmcnt(1)
	v_mfma_f32_16x16x32_bf16 v[68:71], v[40:43], v[36:39], v[44:47]
	ds_read_b128 v[40:43], v207 offset:64
	s_waitcnt lgkmcnt(1)
	v_mfma_f32_16x16x32_bf16 v[44:47], v[48:51], v[84:87], 0
	ds_read_b128 v[48:51], v209
	s_waitcnt lgkmcnt(1)
	v_mfma_f32_16x16x32_bf16 v[64:67], v[40:43], v[36:39], v[44:47]
	ds_read_b128 v[40:43], v209 offset:64
	s_waitcnt lgkmcnt(1)
	v_mfma_f32_16x16x32_bf16 v[44:47], v[48:51], v[84:87], 0
	ds_read_b128 v[48:51], v210
	s_waitcnt lgkmcnt(1)
	v_mfma_f32_16x16x32_bf16 v[54:57], v[40:43], v[36:39], v[44:47]
	ds_read_b128 v[40:43], v210 offset:64
	s_waitcnt lgkmcnt(1)
	v_mfma_f32_16x16x32_bf16 v[44:47], v[48:51], v[84:87], 0
	ds_read_b128 v[48:51], v211
	s_waitcnt lgkmcnt(1)
	v_mfma_f32_16x16x32_bf16 v[58:61], v[40:43], v[36:39], v[44:47]
	ds_read_b128 v[40:43], v211 offset:64
	s_waitcnt lgkmcnt(1)
	v_mfma_f32_16x16x32_bf16 v[44:47], v[48:51], v[84:87], 0
	s_waitcnt lgkmcnt(0)
	v_mfma_f32_16x16x32_bf16 v[46:49], v[40:43], v[36:39], v[44:47]
	ds_read_b128 v[40:43], v212
	ds_read_b128 v[50:53], v212 offset:64
	ds_read_b128 v[88:91], v213
	ds_read_b128 v[92:95], v213 offset:64
	ds_read_b128 v[96:99], v216
	s_waitcnt lgkmcnt(4)
	v_mfma_f32_16x16x32_bf16 v[40:43], v[40:43], v[84:87], 0
	s_waitcnt lgkmcnt(2)
	v_mfma_f32_16x16x32_bf16 v[88:91], v[88:91], v[84:87], 0
	v_mfma_f32_16x16x32_bf16 v[50:53], v[50:53], v[36:39], v[40:43]
	s_nop 4
	ds_read_b128 v[40:43], v214
	s_waitcnt lgkmcnt(2)
	v_mfma_f32_16x16x32_bf16 v[118:121], v[92:95], v[36:39], v[88:91]
	ds_read_b128 v[92:95], v215
	s_nop 1
	ds_read_b128 v[88:91], v214 offset:64
	s_waitcnt lgkmcnt(2)
	v_mfma_f32_16x16x32_bf16 v[40:43], v[40:43], v[84:87], 0
	s_waitcnt lgkmcnt(0)
	v_mfma_f32_16x16x32_bf16 v[42:45], v[88:91], v[36:39], v[40:43]
	ds_read_b128 v[88:91], v215 offset:64
	v_mfma_f32_16x16x32_bf16 v[92:95], v[92:95], v[84:87], 0
	s_waitcnt lgkmcnt(0)
	v_mfma_f32_16x16x32_bf16 v[114:117], v[88:91], v[36:39], v[92:95]
	ds_read_b128 v[88:91], v216 offset:64
	v_mfma_f32_16x16x32_bf16 v[92:95], v[96:99], v[84:87], 0
	ds_read_b128 v[96:99], v217
	s_waitcnt lgkmcnt(1)
	v_mfma_f32_16x16x32_bf16 v[110:113], v[88:91], v[36:39], v[92:95]
	ds_read_b128 v[88:91], v217 offset:64
	s_waitcnt lgkmcnt(1)
	v_mfma_f32_16x16x32_bf16 v[92:95], v[96:99], v[84:87], 0
	ds_read_b128 v[96:99], v218
	s_waitcnt lgkmcnt(1)
	v_mfma_f32_16x16x32_bf16 v[106:109], v[88:91], v[36:39], v[92:95]
	ds_read_b128 v[88:91], v218 offset:64
	s_waitcnt lgkmcnt(1)
	v_mfma_f32_16x16x32_bf16 v[92:95], v[96:99], v[84:87], 0
	ds_read_b128 v[96:99], v219
	s_waitcnt lgkmcnt(1)
	v_mfma_f32_16x16x32_bf16 v[102:105], v[88:91], v[36:39], v[92:95]
	ds_read_b128 v[88:91], v219 offset:64
	s_waitcnt lgkmcnt(1)
	v_mfma_f32_16x16x32_bf16 v[92:95], v[96:99], v[84:87], 0
	s_waitcnt lgkmcnt(0)
	v_mfma_f32_16x16x32_bf16 v[98:101], v[88:91], v[36:39], v[92:95]
	ds_read_b128 v[88:91], v220
	s_nop 4
	ds_read_b128 v[92:95], v220 offset:64
	s_waitcnt lgkmcnt(1)
	v_mfma_f32_16x16x32_bf16 v[84:87], v[88:91], v[84:87], 0
	s_waitcnt lgkmcnt(0)
	v_mfma_f32_16x16x32_bf16 v[94:97], v[92:95], v[36:39], v[84:87]
	v_max_f32_e32 v1, v81, v81
	v_max_f32_e32 v3, v80, v80
	v_max_f32_e32 v1, v3, v1
	v_max3_f32 v1, v1, v82, v83
	v_max3_f32 v1, v1, v76, v77
	v_max3_f32 v1, v1, v78, v79
	v_max3_f32 v1, v1, v72, v73
	v_max3_f32 v1, v1, v74, v75
	v_max3_f32 v1, v1, v68, v69
	v_max3_f32 v1, v1, v70, v71
	v_max3_f32 v1, v1, v64, v65
	v_max3_f32 v1, v1, v66, v67
	v_max3_f32 v1, v1, v54, v55
	v_max3_f32 v1, v1, v56, v57
	v_max3_f32 v1, v1, v58, v59
	v_max3_f32 v1, v1, v60, v61
	v_max3_f32 v1, v1, v46, v47
	v_max3_f32 v1, v1, v48, v49
	v_max3_f32 v1, v1, v50, v51
	v_max3_f32 v1, v1, v52, v53
	v_max3_f32 v1, v1, v118, v119
	v_max3_f32 v1, v1, v120, v121
	v_max3_f32 v1, v1, v42, v43
	v_max3_f32 v1, v1, v44, v45
	v_max3_f32 v1, v1, v114, v115
	v_max3_f32 v1, v1, v116, v117
	v_max3_f32 v1, v1, v110, v111
	v_max3_f32 v1, v1, v112, v113
	v_max3_f32 v1, v1, v106, v107
	v_max3_f32 v1, v1, v108, v109
	v_max3_f32 v1, v1, v102, v103
	v_max3_f32 v1, v1, v104, v105
	v_and_b32_e32 v36, 64, v223
	v_max3_f32 v1, v1, v98, v99
	v_xor_b32_e32 v3, 16, v223
	v_add_u32_e32 v227, 64, v36
	v_max3_f32 v1, v1, v100, v101
	v_cmp_lt_i32_e32 vcc, v3, v227
	v_max3_f32 v1, v1, v94, v95
	v_max3_f32 v1, v1, v96, v97
	v_cndmask_b32_e32 v3, v223, v3, vcc
	v_lshlrev_b32_e32 v129, 2, v3
	v_mov_b32_e32 v186, v1
	s_add_i32 s35, s35, 1
	v_cvt_f32_u32_e32 v36, s35
	v_cvt_f32_i32_e32 v162, v0
	v_mul_f32_e32 v135, s20, v224
	v_permlane16_swap_b32_e32 v186, v1
	v_max_f32_e32 v1, v1, v186
	v_xor_b32_e32 v3, 32, v223
	v_cmp_lt_i32_e32 vcc, v3, v227
	v_exp_f32_e64 v36, -v36
	s_mov_b32 s20, 0xc2e00000
	v_cndmask_b32_e32 v3, v223, v3, vcc
	v_lshlrev_b32_e32 v131, 2, v3
	v_mov_b32_e32 v186, v1
	v_mul_f32_e32 v166, 0x3fb8aa3b, v36
	s_cmp_gt_i32 s34, 14
	s_nop 0
	v_permlane32_swap_b32_e32 v186, v1
	v_max_f32_e32 v0, v1, v186
	v_mul_f32_e32 v0, 0x3e38aa3b, v0
	v_max_f32_e32 v137, v0, v135
	v_fma_f32 v3, v166, v162, v137
	v_fma_f32 v1, v166, s43, -v3
	v_fma_f32 v0, v166, s42, -v3
	v_fmac_f32_e32 v1, 0x3e38aa3b, v81
	v_fmac_f32_e32 v0, 0x3e38aa3b, v80
	v_exp_f32_e32 v36, v1
	v_exp_f32_e32 v37, v0
	v_pk_add_f32 v[0:1], v[162:163], s[42:43] op_sel_hi:[0,1] neg_lo:[1,0] neg_hi:[1,0]
	v_cmp_le_f32_e64 vcc, |v1|, s44
	v_fma_f32 v1, v166, s47, -v3
	v_fmac_f32_e32 v1, 0x3e38aa3b, v83
	v_cndmask_b32_e32 v163, 0, v36, vcc
	v_cmp_le_f32_e64 vcc, |v0|, s44
	v_fma_f32 v0, v166, s46, -v3
	v_exp_f32_e32 v36, v1
	v_fmac_f32_e32 v0, 0x3e38aa3b, v82
	v_cndmask_b32_e32 v165, 0, v37, vcc
	v_exp_f32_e32 v37, v0
	v_pk_add_f32 v[0:1], v[162:163], s[46:47] op_sel_hi:[0,1] neg_lo:[1,0] neg_hi:[1,0]
	v_cmp_le_f32_e64 vcc, |v1|, s44
	v_fma_f32 v228, v166, v162, -v137
	v_fmamk_f32 v1, v166, 0xc2c20000, v228
	v_cndmask_b32_e32 v93, 0, v36, vcc
	v_cmp_le_f32_e64 vcc, |v0|, s44
	v_fma_f32 v0, v166, s20, -v3
	v_fmac_f32_e32 v0, 0x3e38aa3b, v76
	s_mov_b32 s20, 0xc2de0000
	v_exp_f32_e32 v90, v0
	v_fma_f32 v0, v166, s20, -v3
	v_fmac_f32_e32 v0, 0x3e38aa3b, v77
	s_mov_b32 s20, 0xc2dc0000
	v_exp_f32_e32 v89, v0
	v_fma_f32 v0, v166, s20, -v3
	v_fmac_f32_e32 v0, 0x3e38aa3b, v78
	s_mov_b32 s20, 0xc2da0000
	v_exp_f32_e32 v92, v0
	v_fma_f32 v0, v166, s20, -v3
	v_fmac_f32_e32 v0, 0x3e38aa3b, v79
	s_mov_b32 s20, 0xc2c00000
	v_exp_f32_e32 v91, v0
	v_fma_f32 v0, v166, s20, -v3
	v_fmac_f32_e32 v0, 0x3e38aa3b, v72
	s_mov_b32 s20, 0xc2be0000
	v_exp_f32_e32 v86, v0
	v_fma_f32 v0, v166, s20, -v3
	v_fmac_f32_e32 v0, 0x3e38aa3b, v73
	v_exp_f32_e32 v85, v0
	v_fma_f32 v0, v166, s71, -v3
	v_fmac_f32_e32 v0, 0x3e38aa3b, v74
	v_exp_f32_e32 v88, v0
	v_fma_f32 v0, v166, s72, -v3
	v_fmac_f32_e32 v0, 0x3e38aa3b, v75
	v_exp_f32_e32 v87, v0
	v_fma_f32 v0, v166, s73, -v3
	v_fmac_f32_e32 v0, 0x3e38aa3b, v68
	v_exp_f32_e32 v82, v0
	v_fma_f32 v0, v166, s74, -v3
	v_fmac_f32_e32 v0, 0x3e38aa3b, v69
	v_exp_f32_e32 v81, v0
	v_fma_f32 v0, v166, s75, -v3
	v_fmac_f32_e32 v0, 0x3e38aa3b, v70
	v_exp_f32_e32 v84, v0
	v_fma_f32 v0, v166, s76, -v3
	v_fmac_f32_e32 v0, 0x3e38aa3b, v71
	v_exp_f32_e32 v83, v0
	v_fma_f32 v0, v166, s77, -v3
	v_fmac_f32_e32 v0, 0x3e38aa3b, v64
	v_exp_f32_e32 v68, v0
	v_fma_f32 v0, v166, s78, -v3
	v_fmac_f32_e32 v0, 0x3e38aa3b, v65
	v_exp_f32_e32 v65, v0
	v_fma_f32 v0, v166, s79, -v3
	v_fmac_f32_e32 v0, 0x3e38aa3b, v66
	v_exp_f32_e32 v72, v0
	v_fma_f32 v0, v166, s80, -v3
	v_fmac_f32_e32 v0, 0x3e38aa3b, v67
	v_exp_f32_e32 v69, v0
	v_fma_f32 v0, v166, s81, -v3
	v_fmac_f32_e32 v0, 0x3e38aa3b, v54
	v_exp_f32_e32 v74, v0
	v_fma_f32 v0, v166, s82, -v3
	v_fmac_f32_e32 v0, 0x3e38aa3b, v55
	v_exp_f32_e32 v73, v0
	v_fma_f32 v0, v166, s83, -v3
	v_fmac_f32_e32 v0, 0x3e38aa3b, v56
	v_exp_f32_e32 v80, v0
	v_fma_f32 v0, v166, s84, -v3
	v_fmac_f32_e32 v0, 0x3e38aa3b, v57
	v_exp_f32_e32 v79, v0
	v_fma_f32 v0, v166, s85, -v3
	v_fmac_f32_e32 v0, 0x3e38aa3b, v58
	v_exp_f32_e32 v58, v0
	v_fma_f32 v0, v166, s86, -v3
	v_fmac_f32_e32 v0, 0x3e38aa3b, v59
	v_exp_f32_e32 v57, v0
	v_fma_f32 v0, v166, s87, -v3
	v_fmac_f32_e32 v0, 0x3e38aa3b, v60
	v_exp_f32_e32 v64, v0
	v_fma_f32 v0, v166, s88, -v3
	v_fmac_f32_e32 v0, 0x3e38aa3b, v61
	v_exp_f32_e32 v61, v0
	v_fma_f32 v0, v166, s89, -v3
	v_fmac_f32_e32 v0, 0x3e38aa3b, v46
	v_exp_f32_e32 v66, v0
	v_fma_f32 v0, v166, s90, -v3
	v_fmac_f32_e32 v0, 0x3e38aa3b, v47
	v_exp_f32_e32 v63, v0
	v_fma_f32 v0, v166, s91, -v3
	v_fmac_f32_e32 v0, 0x3e38aa3b, v48
	v_exp_f32_e32 v70, v0
	v_fma_f32 v0, v166, s92, -v3
	v_fmac_f32_e32 v0, 0x3e38aa3b, v49
	v_exp_f32_e32 v67, v0
	v_sub_f32_e32 v0, 0, v162
	v_fma_f32 v0, |v0|, v166, v137
	v_fma_f32 v0, v50, s70, -v0
	v_exp_f32_e32 v50, v0
	v_sub_f32_e32 v0, 1.0, v162
	v_fma_f32 v0, |v0|, v166, v137
	v_fma_f32 v0, v51, s70, -v0
	v_exp_f32_e32 v49, v0
	v_sub_f32_e32 v0, 2.0, v162
	v_fma_f32 v0, |v0|, v166, v137
	v_fma_f32 v0, v52, s70, -v0
	v_exp_f32_e32 v54, v0
	v_sub_f32_e32 v0, 0x40400000, v162
	v_fma_f32 v0, |v0|, v166, v137
	v_fma_f32 v0, v53, s70, -v0
	v_exp_f32_e32 v53, v0
	v_fmamk_f32 v0, v166, 0xc1800000, v228
	v_fmac_f32_e32 v0, 0x3e38aa3b, v118
	v_exp_f32_e32 v56, v0
	v_fmamk_f32 v0, v166, 0xc1880000, v228
	v_fmac_f32_e32 v0, 0x3e38aa3b, v119
	v_exp_f32_e32 v55, v0
	v_fmamk_f32 v0, v166, 0xc1900000, v228
	v_fmac_f32_e32 v0, 0x3e38aa3b, v120
	v_exp_f32_e32 v62, v0
	v_fmamk_f32 v0, v166, 0xc1980000, v228
	v_fmac_f32_e32 v0, 0x3e38aa3b, v121
	v_exp_f32_e32 v59, v0
	v_fmamk_f32 v0, v166, 0xc2000000, v228
	v_fmac_f32_e32 v0, 0x3e38aa3b, v42
	v_exp_f32_e32 v42, v0
	v_fmamk_f32 v0, v166, 0xc2040000, v228
	v_fmac_f32_e32 v0, 0x3e38aa3b, v43
	v_exp_f32_e32 v41, v0
	v_fmamk_f32 v0, v166, 0xc2080000, v228
	v_fmac_f32_e32 v0, 0x3e38aa3b, v44
	v_exp_f32_e32 v46, v0
	v_fmamk_f32 v0, v166, 0xc20c0000, v228
	v_fmac_f32_e32 v0, 0x3e38aa3b, v45
	v_exp_f32_e32 v45, v0
	v_fmamk_f32 v0, v166, 0xc2400000, v228
	v_fmac_f32_e32 v0, 0x3e38aa3b, v114
	v_exp_f32_e32 v48, v0
	v_fmamk_f32 v0, v166, 0xc2440000, v228
	v_fmac_f32_e32 v0, 0x3e38aa3b, v115
	v_exp_f32_e32 v47, v0
	v_fmamk_f32 v0, v166, 0xc2480000, v228
	v_fmac_f32_e32 v0, 0x3e38aa3b, v116
	v_exp_f32_e32 v52, v0
	v_fmamk_f32 v0, v166, 0xc24c0000, v228
	v_fmac_f32_e32 v0, 0x3e38aa3b, v117
	v_exp_f32_e32 v51, v0
	v_fmamk_f32 v0, v166, 0xc2800000, v228
	v_fmac_f32_e32 v0, 0x3e38aa3b, v110
	v_exp_f32_e32 v36, v0
	v_fmamk_f32 v0, v166, 0xc2820000, v228
	v_fmac_f32_e32 v0, 0x3e38aa3b, v111
	v_exp_f32_e32 v3, v0
	v_fmamk_f32 v0, v166, 0xc2840000, v228
	v_fmac_f32_e32 v0, 0x3e38aa3b, v112
	v_exp_f32_e32 v38, v0
	v_fmamk_f32 v0, v166, 0xc2860000, v228
	v_fmac_f32_e32 v0, 0x3e38aa3b, v113
	v_cndmask_b32_e32 v167, 0, v37, vcc
	v_exp_f32_e32 v37, v0
	v_fmamk_f32 v0, v166, 0xc2a00000, v228
	v_fmac_f32_e32 v0, 0x3e38aa3b, v106
	v_exp_f32_e32 v40, v0
	v_fmamk_f32 v0, v166, 0xc2a20000, v228
	v_fmac_f32_e32 v0, 0x3e38aa3b, v107
	v_exp_f32_e32 v39, v0
	v_fmamk_f32 v0, v166, 0xc2a40000, v228
	v_fmac_f32_e32 v0, 0x3e38aa3b, v108
	v_exp_f32_e32 v44, v0
	v_fmamk_f32 v0, v166, 0xc2a60000, v228
	v_fmac_f32_e32 v0, 0x3e38aa3b, v109
	v_fmamk_f32 v77, v166, 0xc3010000, v228
	v_exp_f32_e32 v43, v0
	v_fmamk_f32 v0, v166, 0xc2c00000, v228
	v_fmamk_f32 v78, v166, 0xc2e20000, v228
	v_fmamk_f32 v76, v166, 0xc3000000, v228
	v_fmac_f32_e32 v77, 0x3e38aa3b, v95
	v_fmac_f32_e32 v0, 0x3e38aa3b, v102
	v_fmamk_f32 v60, v166, 0xc2c40000, v228
	v_fmamk_f32 v71, v166, 0xc2c60000, v228
	v_fmamk_f32 v75, v166, 0xc2e00000, v228
	v_fmac_f32_e32 v78, 0x3e38aa3b, v99
	v_fmamk_f32 v99, v166, 0xc2e40000, v228
	v_fmamk_f32 v102, v166, 0xc2e60000, v228
	v_fmac_f32_e32 v76, 0x3e38aa3b, v94
	v_fmamk_f32 v95, v166, 0xc3020000, v228
	v_fmac_f32_e32 v228, 0xc3030000, v166
	v_exp_f32_e32 v94, v77
	v_fmac_f32_e32 v95, 0x3e38aa3b, v96
	v_fmac_f32_e32 v228, 0x3e38aa3b, v97
	v_exp_f32_e32 v96, v76
	v_pk_add_f32 v[76:77], v[162:163], s[44:45] op_sel_hi:[0,1] neg_lo:[1,0] neg_hi:[1,0]
	v_exp_f32_e32 v97, v228
	v_cmp_le_f32_e64 vcc, |v77|, s44
	v_fmac_f32_e32 v1, 0x3e38aa3b, v103
	v_fmac_f32_e32 v60, 0x3e38aa3b, v104
	v_cndmask_b32_e32 v94, 0, v94, vcc
	v_cmp_le_f32_e64 vcc, |v76|, s44
	v_pk_add_f32 v[76:77], v[162:163], s[48:49] op_sel_hi:[0,1] neg_lo:[1,0] neg_hi:[1,0]
	v_fmac_f32_e32 v71, 0x3e38aa3b, v105
	v_fmac_f32_e32 v75, 0x3e38aa3b, v98
	v_fmac_f32_e32 v99, 0x3e38aa3b, v100
	v_fmac_f32_e32 v102, 0x3e38aa3b, v101
	v_cndmask_b32_e32 v96, 0, v96, vcc
	v_exp_f32_e32 v95, v95
	v_cmp_le_f32_e64 vcc, |v77|, s44
	v_exp_f32_e32 v0, v0
	v_exp_f32_e32 v1, v1
	v_exp_f32_e32 v60, v60
	v_cndmask_b32_e32 v98, 0, v97, vcc
	v_cmp_le_f32_e64 vcc, |v76|, s44
	v_exp_f32_e32 v71, v71
	v_exp_f32_e32 v76, v75
	v_exp_f32_e32 v75, v78
	v_exp_f32_e32 v78, v99
	v_exp_f32_e32 v77, v102
	v_cndmask_b32_e32 v100, 0, v95, vcc
	s_mov_b64 s[20:21], -1
	s_cbranch_scc1 .LBB0_410
	s_cmp_eq_u32 s34, 0
	s_cselect_b64 s[20:21], -1, 0

.LBB0_412:
	v_add_u32_e32 v230, v182, v183
	v_add_u32_e32 v231, v182, v184
	v_add_u32_e32 v232, v182, v185
	v_add_u32_e32 v233, v182, v174
	v_add_u32_e32 v230, 0xe000, v230
	v_add_u32_e32 v231, 0xe000, v231
	v_add_u32_e32 v232, 0xe000, v232
	v_add_u32_e32 v233, 0xe000, v233
	ds_read2_b64 v[106:109], v230 offset0:32 offset1:36
	ds_read2_b64 v[110:113], v231 offset0:32 offset1:36
	ds_read2_b64 v[114:117], v232 offset0:32 offset1:36
	ds_read2_b64 v[118:121], v233 offset0:32 offset1:36
	ds_read2_b64 v[234:237], v230 offset0:40 offset1:44
	ds_read2_b64 v[238:241], v231 offset0:40 offset1:44
	ds_read2_b64 v[242:245], v232 offset0:40 offset1:44
	ds_read2_b64 v[246:249], v233 offset0:40 offset1:44
	v_pk_add_f32 v[228:229], v[0:1], v[42:43]
	v_pk_add_f32 v[102:103], v[36:37], v[44:45]
	v_pk_add_f32 v[104:105], v[38:39], v[46:47]
	v_pk_add_f32 v[250:251], v[40:41], v[48:49]
	v_pk_add_f32 v[228:229], v[228:229], v[50:51]
	v_pk_add_f32 v[102:103], v[102:103], v[52:53]
	v_pk_add_f32 v[104:105], v[104:105], v[54:55]
	v_pk_add_f32 v[250:251], v[250:251], v[56:57]
	v_pk_add_f32 v[228:229], v[228:229], v[58:59]
	v_pk_add_f32 v[102:103], v[102:103], v[60:61]
	v_pk_add_f32 v[104:105], v[104:105], v[62:63]
	v_pk_add_f32 v[250:251], v[250:251], v[64:65]
	v_pk_add_f32 v[228:229], v[228:229], v[66:67]
	v_pk_add_f32 v[102:103], v[102:103], v[68:69]
	v_pk_add_f32 v[104:105], v[104:105], v[70:71]
	v_pk_add_f32 v[250:251], v[250:251], v[72:73]
	v_pk_add_f32 v[228:229], v[228:229], v[74:75]
	v_pk_add_f32 v[102:103], v[102:103], v[76:77]
	v_pk_add_f32 v[104:105], v[104:105], v[78:79]
	v_pk_add_f32 v[250:251], v[250:251], v[80:81]
	v_pk_add_f32 v[228:229], v[228:229], v[82:83]
	v_pk_add_f32 v[102:103], v[102:103], v[84:85]
	v_pk_add_f32 v[104:105], v[104:105], v[86:87]
	v_pk_add_f32 v[250:251], v[250:251], v[88:89]
	v_pk_add_f32 v[228:229], v[228:229], v[90:91]
	v_pk_add_f32 v[102:103], v[102:103], v[92:93]
	v_pk_add_f32 v[228:229], v[228:229], v[102:103]
	v_pk_add_f32 v[104:105], v[104:105], v[250:251]
	v_pk_add_f32 v[228:229], v[228:229], v[104:105]
	v_add_f32_e32 v228, v228, v3
	v_add_f32_e32 v229, v229, v163
	v_add_f32_e32 v228, v228, v165
	v_add_f32_e32 v229, v229, v167
	v_add_f32_e32 v228, v228, v94
	v_add_f32_e32 v229, v229, v96
	v_add_f32_e32 v228, v228, v98
	v_add_f32_e32 v229, v229, v100
	v_add_f32_e32 v162, v228, v229
	v_mov_b32_e32 v95, v162
	v_cvt_pk_bf16_f32 v102, v165, v163
	v_cvt_pk_bf16_f32 v103, v167, v93
	v_cvt_pk_bf16_f32 v104, v90, v89
	v_cvt_pk_bf16_f32 v105, v92, v91
	v_permlane16_swap_b32_e32 v95, v162
	v_add_f32_e32 v162, v162, v95
	v_sub_f32_e32 v97, v135, v137
	v_exp_f32_e32 v97, v97
	v_mov_b32_e32 v95, v162
	v_cvt_pk_bf16_f32 v250, v86, v85
	v_cvt_pk_bf16_f32 v251, v88, v87
	v_cvt_pk_bf16_f32 v252, v82, v81
	v_cvt_pk_bf16_f32 v253, v84, v83
	v_permlane32_swap_b32_e32 v95, v162
	v_add_f32_e32 v162, v162, v95
	s_waitcnt lgkmcnt(0)
	v_add_f32_e32 v95, v97, v162
	v_mfma_f32_16x16x32_bf16 v[164:167], v[106:109], v[102:105], 0
	v_mfma_f32_16x16x32_bf16 v[90:93], v[110:113], v[102:105], 0
	v_mfma_f32_16x16x32_bf16 v[82:85], v[114:117], v[102:105], 0
	v_mfma_f32_16x16x32_bf16 v[86:89], v[118:121], v[102:105], 0
	ds_read2_b64 v[106:109], v230 offset0:48 offset1:52
	ds_read2_b64 v[110:113], v231 offset0:48 offset1:52
	ds_read2_b64 v[114:117], v232 offset0:48 offset1:52
	ds_read2_b64 v[118:121], v233 offset0:48 offset1:52
	v_cvt_pk_bf16_f32 v102, v68, v65
	v_cvt_pk_bf16_f32 v103, v72, v69
	v_cvt_pk_bf16_f32 v104, v74, v73
	v_cvt_pk_bf16_f32 v105, v80, v79
	v_mfma_f32_16x16x32_bf16 v[164:167], v[234:237], v[250:253], v[164:167]
	v_mfma_f32_16x16x32_bf16 v[90:93], v[238:241], v[250:253], v[90:93]
	v_mfma_f32_16x16x32_bf16 v[82:85], v[242:245], v[250:253], v[82:85]
	v_mfma_f32_16x16x32_bf16 v[86:89], v[246:249], v[250:253], v[86:89]
	ds_read2_b64 v[234:237], v230 offset0:56 offset1:60
	ds_read2_b64 v[238:241], v231 offset0:56 offset1:60
	ds_read2_b64 v[242:245], v232 offset0:56 offset1:60
	ds_read2_b64 v[246:249], v233 offset0:56 offset1:60
	v_cvt_pk_bf16_f32 v250, v58, v57
	v_cvt_pk_bf16_f32 v251, v64, v61
	v_cvt_pk_bf16_f32 v252, v66, v63
	v_cvt_pk_bf16_f32 v253, v70, v67
	s_waitcnt lgkmcnt(4)
	v_mfma_f32_16x16x32_bf16 v[164:167], v[106:109], v[102:105], v[164:167]
	v_mfma_f32_16x16x32_bf16 v[90:93], v[110:113], v[102:105], v[90:93]
	v_mfma_f32_16x16x32_bf16 v[82:85], v[114:117], v[102:105], v[82:85]
	v_mfma_f32_16x16x32_bf16 v[86:89], v[118:121], v[102:105], v[86:89]
	ds_read2_b64 v[106:109], v230 offset0:64 offset1:68
	ds_read2_b64 v[110:113], v231 offset0:64 offset1:68
	ds_read2_b64 v[114:117], v232 offset0:64 offset1:68
	ds_read2_b64 v[118:121], v233 offset0:64 offset1:68
	v_cvt_pk_bf16_f32 v102, v50, v49
	v_cvt_pk_bf16_f32 v103, v54, v53
	v_cvt_pk_bf16_f32 v104, v56, v55
	v_cvt_pk_bf16_f32 v105, v62, v59
	s_waitcnt lgkmcnt(4)
	v_mfma_f32_16x16x32_bf16 v[164:167], v[234:237], v[250:253], v[164:167]
	v_mfma_f32_16x16x32_bf16 v[90:93], v[238:241], v[250:253], v[90:93]
	v_mfma_f32_16x16x32_bf16 v[82:85], v[242:245], v[250:253], v[82:85]
	v_mfma_f32_16x16x32_bf16 v[86:89], v[246:249], v[250:253], v[86:89]
	ds_read2_b64 v[234:237], v230 offset0:72 offset1:76
	ds_read2_b64 v[238:241], v231 offset0:72 offset1:76
	ds_read2_b64 v[242:245], v232 offset0:72 offset1:76
	ds_read2_b64 v[246:249], v233 offset0:72 offset1:76
	v_cvt_pk_bf16_f32 v250, v42, v41
	v_cvt_pk_bf16_f32 v251, v46, v45
	v_cvt_pk_bf16_f32 v252, v48, v47
	v_cvt_pk_bf16_f32 v253, v52, v51
	s_waitcnt lgkmcnt(4)
	v_mfma_f32_16x16x32_bf16 v[164:167], v[106:109], v[102:105], v[164:167]
	v_mfma_f32_16x16x32_bf16 v[90:93], v[110:113], v[102:105], v[90:93]
	v_mfma_f32_16x16x32_bf16 v[82:85], v[114:117], v[102:105], v[82:85]
	v_mfma_f32_16x16x32_bf16 v[86:89], v[118:121], v[102:105], v[86:89]
	ds_read2_b64 v[106:109], v230 offset0:80 offset1:84
	ds_read2_b64 v[110:113], v231 offset0:80 offset1:84
	ds_read2_b64 v[114:117], v232 offset0:80 offset1:84
	ds_read2_b64 v[118:121], v233 offset0:80 offset1:84
	v_cvt_pk_bf16_f32 v102, v36, v3
	v_cvt_pk_bf16_f32 v103, v38, v37
	v_cvt_pk_bf16_f32 v104, v40, v39
	v_cvt_pk_bf16_f32 v105, v44, v43
	s_waitcnt lgkmcnt(4)
	v_mfma_f32_16x16x32_bf16 v[164:167], v[234:237], v[250:253], v[164:167]
	v_mfma_f32_16x16x32_bf16 v[90:93], v[238:241], v[250:253], v[90:93]
	v_mfma_f32_16x16x32_bf16 v[82:85], v[242:245], v[250:253], v[82:85]
	v_mfma_f32_16x16x32_bf16 v[86:89], v[246:249], v[250:253], v[86:89]
	ds_read2_b64 v[234:237], v230 offset0:88 offset1:92
	ds_read2_b64 v[238:241], v231 offset0:88 offset1:92
	ds_read2_b64 v[242:245], v232 offset0:88 offset1:92
	ds_read2_b64 v[246:249], v233 offset0:88 offset1:92
	v_cvt_pk_bf16_f32 v250, v0, v1
	v_cvt_pk_bf16_f32 v251, v60, v71
	v_cvt_pk_bf16_f32 v252, v76, v75
	v_cvt_pk_bf16_f32 v253, v78, v77
	v_rcp_f32_e32 v56, v95
	s_waitcnt lgkmcnt(4)
	v_mfma_f32_16x16x32_bf16 v[164:167], v[106:109], v[102:105], v[164:167]
	v_mfma_f32_16x16x32_bf16 v[90:93], v[110:113], v[102:105], v[90:93]
	v_mfma_f32_16x16x32_bf16 v[82:85], v[114:117], v[102:105], v[82:85]
	v_mfma_f32_16x16x32_bf16 v[86:89], v[118:121], v[102:105], v[86:89]
	ds_read2_b64 v[106:109], v230 offset0:96 offset1:100
	ds_read2_b64 v[110:113], v231 offset0:96 offset1:100
	ds_read2_b64 v[114:117], v232 offset0:96 offset1:100
	ds_read2_b64 v[118:121], v233 offset0:96 offset1:100
	v_cvt_pk_bf16_f32 v102, v96, v94
	v_cvt_pk_bf16_f32 v103, v100, v98
	v_mov_b32_e32 v104, v2
	v_mov_b32_e32 v105, v2
	s_waitcnt lgkmcnt(4)
	v_mfma_f32_16x16x32_bf16 v[164:167], v[234:237], v[250:253], v[164:167]
	v_mfma_f32_16x16x32_bf16 v[90:93], v[238:241], v[250:253], v[90:93]
	v_mfma_f32_16x16x32_bf16 v[82:85], v[242:245], v[250:253], v[82:85]
	v_mfma_f32_16x16x32_bf16 v[86:89], v[246:249], v[250:253], v[86:89]
	s_waitcnt lgkmcnt(0)
	v_mfma_f32_16x16x32_bf16 v[40:43], v[106:109], v[102:105], v[164:167]
	v_mfma_f32_16x16x32_bf16 v[44:47], v[110:113], v[102:105], v[90:93]
	v_mfma_f32_16x16x32_bf16 v[48:51], v[114:117], v[102:105], v[82:85]
	v_mfma_f32_16x16x32_bf16 v[36:39], v[118:121], v[102:105], v[86:89]
	v_mov_b32_e32 v3, v2
	s_nop 3
	v_mul_f32_e64 v40, v56, v40
	v_mul_f32_e64 v41, v56, v41
	v_pk_mul_f32 v[0:1], v[56:57], v[42:43] op_sel_hi:[0,1]
	v_pk_mul_f32 v[42:43], v[40:41], v[40:41]
	v_cvt_pk_bf16_f32 v40, v40, v41
	v_cvt_pk_bf16_f32 v41, v0, v1
	v_pk_mul_f32 v[52:53], v[0:1], v[0:1]
	global_store_dwordx2 v[160:161], v[40:41], off offset:-64
	v_pk_mul_f32 v[0:1], v[56:57], v[46:47] op_sel_hi:[0,1]
	v_pk_mul_f32 v[40:41], v[56:57], v[44:45] op_sel_hi:[0,1]
	v_pk_mov_b32 v[54:55], v[42:43], v[52:53] op_sel:[1,0]
	v_mov_b32_e32 v43, v53
	v_pk_mul_f32 v[44:45], v[40:41], v[40:41]
	v_pk_mul_f32 v[46:47], v[0:1], v[0:1]
	v_pk_add_f32 v[42:43], v[54:55], v[42:43]
	v_pk_mov_b32 v[52:53], v[44:45], v[46:47] op_sel:[1,0]
	v_mov_b32_e32 v45, v47
	v_add_f32_e32 v3, v42, v43
	v_pk_add_f32 v[44:45], v[52:53], v[44:45]
	v_pk_mul_f32 v[36:37], v[56:57], v[36:37] op_sel_hi:[0,1]
	v_add_f32_e32 v42, v133, v3
	v_cvt_pk_bf16_f32 v40, v40, v41
	v_cvt_pk_bf16_f32 v41, v0, v1
	v_mul_f32_e32 v3, v37, v37
	v_pk_add_f32 v[44:45], v[44:45], v[44:45] op_sel:[0,1] op_sel_hi:[1,0]
	global_store_dwordx2 v[160:161], v[40:41], off offset:-32
	v_pk_mul_f32 v[40:41], v[56:57], v[48:49] op_sel_hi:[0,1]
	v_mul_f32_e32 v43, v36, v36
	v_mov_b32_e32 v45, v3
	v_pk_mul_f32 v[0:1], v[56:57], v[50:51] op_sel_hi:[0,1]
	v_pk_add_f32 v[42:43], v[42:43], v[44:45]
	v_mul_f32_e32 v44, v41, v41
	v_cvt_pk_bf16_f32 v46, v40, v41
	v_cvt_pk_bf16_f32 v47, v0, v1
	v_pk_mul_f32 v[38:39], v[56:57], v[38:39] op_sel_hi:[0,1]
	v_pk_fma_f32 v[40:41], v[40:41], v[40:41], v[44:45] op_sel_hi:[1,1,0]
	v_mul_f32_e32 v44, v1, v1
	global_store_dwordx2 v[160:161], v[46:47], off
	v_mul_f32_e32 v46, v38, v38
	v_mul_f32_e32 v47, v39, v39
	v_pk_fma_f32 v[0:1], v[0:1], v[0:1], v[44:45] op_sel_hi:[1,1,0]
	v_mov_b32_e32 v41, v46
	v_mov_b32_e32 v1, v47
	v_pk_add_f32 v[0:1], v[40:41], v[0:1]
	s_add_i32 s64, s64, 64
	v_pk_add_f32 v[0:1], v[42:43], v[0:1]
	s_cmpk_eq_i32 s64, 0x100
	v_add_f32_e32 v133, v0, v1
	v_cvt_pk_bf16_f32 v0, v36, v37
	v_cvt_pk_bf16_f32 v1, v38, v39
	global_store_dwordx2 v[160:161], v[0:1], off offset:32
	v_lshl_add_u64 v[160:161], v[160:161], 0, s[50:51]
	s_cbranch_scc1 .LBB0_414
	s_waitcnt vmcnt(4)
	v_mov_b64_e32 v[38:39], v[34:35]
	v_mov_b64_e32 v[36:37], v[32:33]
	s_branch .LBB0_408
